# gdn_scan step: fragment reads bursted per half-step, LDS-DMA split in two groups with 1.5 steps of lead
# baseline (speedup 1.0000x reference)
; DI void gdn_scan(const Params& P, int item, unsigned char* smem) {
;     ...
;     const int r4 = tid >> 4, k16 = (tid & 15) ^ (r4 & 15), k8 = (tid & 7) ^ (r4 & 7);
;     const bf16_t* pw = proj + (tb + r4) * PJ + 768 + h * 128 + k16 * 8;
;     const bf16_t* pq = gq + (tb + r4) * 1536 + h * 128 + k16 * 8;
;     const bf16_t* pk = proj + (tb + (tid >> 3)) * PJ + 1792 + h * 128 + k8 * 8;
;     const bf16_t* pd = proj + (tb + r4) * PJ + 1280 + h * 128 + ((tid >> 3) & 1) * 64 + k8 * 8;
;     const int nu = ns * 32 + ((tid >> 3) & 31);
;     const bf16_t* pu = gq + (tb + (nu >> 1)) * 1536 + 1024 + h * 128 + (nu & 1) * 64 + (tid & 7) * 8;
;     const unsigned lbase = (unsigned)(size_t)smem + (unsigned)__builtin_amdgcn_readfirstlane(wid) * 1024u;
;     const bool uwave = (__builtin_amdgcn_readfirstlane(wid) < 4);
;     ...
;     const int ow = (16 * mi + r16) * 256, oqk = SC_QK + (16 * mi + r16) * 128, okd = SC_KD + (16 * md + r16) * 128;
;     const int out = SC_UT + (16 * nt + r16) * 128 + (16 * mi + 4 * q4) * 2;
;     const int x8 = r16 >> 1;
;     f32x4 accS[2] = {{0.f, 0.f, 0.f, 0.f}, {0.f, 0.f, 0.f, 0.f}};
;     SC_ISSUE(0);
;     asm volatile("s_waitcnt vmcnt(0)" ::: "memory");
;     __syncthreads();
.LBB0_72:
	v_bfi_b32 v15, -16, v0, v6
	s_movk_i32 s0, 0x110
	v_mul_lo_u32 v16, v15, s0
	s_movk_i32 s0, 0x90
	v_bfe_u32 v14, v6, 4, 2
	v_lshlrev_b32_e32 v31, 7, v15
	v_mul_lo_u32 v15, v15, s0
	v_readlane_b32 s0, v248, 12
	v_and_b32_e32 v8, 15, v6
	v_lshrrev_b32_e32 v13, 4, v6
	v_lshlrev_b32_e32 v9, 4, v12
	v_readlane_b32 s1, v248, 11
	v_add_u32_e32 v39, s0, v15
	v_lshlrev_b32_e32 v15, 3, v14
	v_lshlrev_b32_e32 v12, 5, v12
	v_add3_u32 v41, s1, v12, v15
	v_bitop3_b32 v12, v13, v8, 3 bitop3:0x6c
	v_lshlrev_b32_e32 v37, 4, v12
	v_bitop3_b32 v12, v14, v8, 4 bitop3:0x36
	v_lshlrev_b32_e32 v36, 4, v12
	v_bitop3_b32 v12, v14, v8, 8 bitop3:0x36
	v_and_b32_e32 v11, 48, v9
	v_bfe_u32 v6, v6, 1, 3
	v_lshlrev_b32_e32 v35, 4, v12
	v_bitop3_b32 v12, v14, v8, 12 bitop3:0x36
	v_or_b32_e32 v10, v11, v8
	v_lshl_or_b32 v27, v14, 2, v11
	v_lshlrev_b32_e32 v11, 1, v11
	v_lshlrev_b32_e32 v33, 4, v12
	v_bitop3_b32 v12, v13, v6, 3 bitop3:0x6c
	s_lshl_b64 s[18:19], s[10:11], 24
	v_lshlrev_b32_e32 v38, 4, v14
	v_add3_u32 v30, v39, v11, v15
	v_lshlrev_b32_e32 v26, 4, v12
	v_bitop3_b32 v6, v14, v6, 4 bitop3:0x36
	v_lshl_or_b32 v12, v27, 11, s18
	v_mov_b32_e32 v13, s19
	v_mad_i64_i32 v[14:15], s[18:19], v0, s75, 0
	v_add_u32_e32 v25, s1, v16
	v_add_u32_e32 v28, s0, v38
	v_mad_i64_i32 v[14:15], s[18:19], s10, v232, v[14:15]
	v_readlane_b32 s0, v249, 34
	v_or_b32_e32 v14, v14, v176
	v_readlane_b32 s1, v249, 35
	v_lshlrev_b32_e32 v34, 8, v10
	v_lshlrev_b32_e32 v29, 7, v10
	v_lshl_add_u64 v[14:15], s[0:1], 0, v[14:15]
	s_mov_b64 s[0:1], 0x30000
	v_and_b32_e32 v10, -16, v0
	v_lshl_add_u64 v[16:17], v[4:5], 0, s[0:1]
	v_mad_i64_i32 v[4:5], s[18:19], v0, s33, 0
	v_and_b32_e32 v0, 0x80, v1
	v_and_b32_e32 v1, 7, v7
	s_lshl_b32 s17, s12, 1
	v_mad_i64_i32 v[4:5], s[10:11], s10, v233, v[4:5]
	v_lshlrev_b32_e32 v1, 4, v1
	v_readlane_b32 s0, v249, 36
	s_and_b32 s17, s17, 0xc0
	v_or3_b32 v0, v4, v0, v1
	v_mov_b32_e32 v1, v5
	v_readlane_b32 s1, v249, 37
	v_ashrrev_i32_e32 v11, 31, v10
	v_or_b32_e32 v12, s17, v12
	v_lshl_add_u64 v[18:19], s[0:1], 0, v[0:1]
	v_readlane_b32 s0, v249, 38
	s_waitcnt vmcnt(0)
	v_lshl_add_u64 v[12:13], v[10:11], 1, v[12:13]
	v_or_b32_e32 v4, v4, v176
	v_readlane_b32 s1, v249, 39
	v_or_b32_e32 v9, v9, v8
	v_lshlrev_b32_e32 v24, 4, v6
	v_mul_u32_u24_e32 v6, 0x90, v8
	v_mul_u32_u24_e32 v42, 0x110, v8
	v_lshl_or_b32 v12, v8, 1, v12
	v_lshl_add_u64 v[20:21], s[0:1], 0, v[4:5]
	s_mov_b64 s[0:1], 0x70000
	v_mov_b32_e32 v4, 0
	v_lshlrev_b32_e32 v9, 7, v9
	v_lshlrev_b32_e32 v32, 1, v27
	v_lshl_add_u64 v[12:13], s[90:91], 0, v[12:13]
	s_add_i32 s10, 0, 0x21400
	v_lshl_add_u64 v[22:23], v[2:3], 0, s[0:1]
	s_mov_b32 s17, 0
	v_add_u32_e32 v40, v25, v38
	v_add_u32_e32 v28, v28, v6
	v_add_u32_e32 v25, v41, v42
	v_mov_b32_e32 v5, v4
	v_mov_b32_e32 v6, v4
	v_mov_b32_e32 v7, v4
	v_mov_b32_e32 v0, v4
	v_mov_b32_e32 v1, v4
	v_mov_b32_e32 v2, v4
	v_mov_b32_e32 v3, v4
	s_mov_b32 s0, 0x5a00000
	s_waitcnt lgkmcnt(0)
	s_barrier
	s_add_i32 s18, s16, 0xf000
	s_mov_b32 m0, s18
	s_mov_b64 s[22:23], 0x38000
	s_mov_b64 s[20:21], 0x18000
	v_lshl_add_u64 v[56:57], v[20:21], 0, s[4:5]
	v_lshl_add_u64 v[58:59], v[56:57], 0, s[22:23]
	global_load_lds_dwordx4 v[56:57], off
	s_add_u32 m0, m0, 0x2000
	v_lshl_add_u64 v[56:57], v[14:15], 0, s[4:5]
	global_load_lds_dwordx4 v[58:59], off
	s_add_u32 m0, m0, 0x2000
	v_lshl_add_u64 v[58:59], v[56:57], 0, s[20:21]
	global_load_lds_dwordx4 v[56:57], off
	s_add_u32 m0, m0, 0x2000
	s_nop 0
	global_load_lds_dwordx4 v[58:59], off
	s_andn2_b64 vcc, exec, s[8:9]
	s_cbranch_vccnz .Lscp_nou
	s_add_u32 m0, m0, 0x8000
	s_nop 0
	global_load_lds_dwordx4 v[16:17], off
	s_branch .Lscp_ud
.Lscp_nou:
	global_load_dword v119, v[16:17], off

; DI float bf_lo(unsigned u) { return __uint_as_float(u << 16); }
; DI float bf_hi(unsigned u) { return __uint_as_float(u & 0xffff0000u); }
; DI u32x2 pack4(const f32x4 a) { u32x2 w; w.x = pk_bf16(a[0], a[1]); w.y = pk_bf16(a[2], a[3]); return w; }
; DI void lds_barrier() { asm volatile("s_waitcnt lgkmcnt(0)\n\ts_barrier" ::: "memory"); }
; DI void gdn_scan(const Params& P, int item, unsigned char* smem) {
;     ...
;     for (int c = 0; c < 128; ++c) {
;         if (c + 1 < 128) SC_ISSUE(c + 1);
;         const unsigned char* sg = smem + (c & 1) * SC_STAGE;
;         f32x4 aP = {0.f, 0.f, 0.f, 0.f}, aO = {0.f, 0.f, 0.f, 0.f};
; #pragma unroll
;         for (int kk = 0; kk < 4; ++kk) {
;             const bf16x8 sf = *(const bf16x8*)(ST + (16 * nt + r16) * 136 + 32 * kk + 8 * q4);
;             const int co = (((4 * kk + q4) ^ r16) << 4);
;             const bf16x8 wf = *(const bf16x8*)(sg + SC_W + ow + co);
;             const bf16x8 qd = *(const bf16x8*)(sg + SC_QD + ow + co);
;             aP = __builtin_amdgcn_mfma_f32_16x16x32_bf16(wf, sf, aP, 0, 0, 0);
;             aO = __builtin_amdgcn_mfma_f32_16x16x32_bf16(qd, sf, aO, 0, 0, 0);
;         }
;         {
;             const u32x2 uu = *(const u32x2*)(sg + out);
;             f32x4 vn;
;             vn[0] = bf_lo(uu.x) - aP[0]; vn[1] = bf_hi(uu.x) - aP[1]; vn[2] = bf_lo(uu.y) - aP[2]; vn[3] = bf_hi(uu.y) - aP[3];
;             *(u32x2*)(VT + (16 * nt + r16) * 72 + 16 * mi + 4 * q4) = pack4(vn);
;         }
;         lds_barrier();
; #pragma unroll
;         for (int ks = 0; ks < 2; ++ks) {
;             const bf16x8 vf = *(const bf16x8*)(VT + (16 * nt + r16) * 72 + 32 * ks + 8 * q4);
;             const bf16x8 qk = *(const bf16x8*)(sg + oqk + (((4 * ks + q4) ^ x8) << 4));
;             aO = __builtin_amdgcn_mfma_f32_16x16x32_bf16(qk, vf, aO, 0, 0, 0);
;         }
.LBB0_74:
	s_add_i32 s11, s17, 1
	s_bitcmp1_b32 s17, 0
	s_cselect_b32 s17, 0xf000, 0
	v_add_u32_e32 v41, s17, v34
	v_add_u32_e32 v50, v41, v37
	v_add_u32_e32 v51, v41, v36
	v_add_u32_e32 v52, v41, v35
	v_add_u32_e32 v53, v41, v33
	v_add3_u32 v54, s17, v31, v32
	ds_read_b128 v[64:67], v40
	ds_read_b128 v[68:71], v50
	ds_read_b128 v[72:75], v50 offset:16384
	ds_read_b128 v[76:79], v40 offset:64
	ds_read_b128 v[80:83], v51
	ds_read_b128 v[84:87], v51 offset:16384
	ds_read_b128 v[88:91], v40 offset:128
	ds_read_b128 v[92:95], v52
	ds_read_b128 v[96:99], v52 offset:16384
	ds_read_b128 v[100:103], v40 offset:192
	ds_read_b128 v[104:107], v53
	ds_read_b128 v[108:111], v53 offset:16384
	ds_read_b64 v[62:63], v54 offset:57344
	s_sub_i32 s18, 0xf000, s17
	s_add_i32 s18, s18, s16
	s_add_i32 s18, s18, 0x8000
	s_mov_b32 m0, s18
	s_mov_b64 s[22:23], 0x38000
	v_lshl_add_u64 v[56:57], v[18:19], 0, s[4:5]
	global_load_lds_dwordx4 v[22:23], off
	s_add_u32 m0, m0, 0x2000
	v_lshl_add_u64 v[58:59], v[56:57], 0, s[22:23]
	global_load_lds_dwordx4 v[56:57], off
	s_add_u32 m0, m0, 0x2000
	s_nop 0
	global_load_lds_dwordx4 v[58:59], off
	s_waitcnt lgkmcnt(11)
	v_mfma_f32_16x16x32_bf16 v[46:49], v[68:71], v[64:67], 0
	s_waitcnt lgkmcnt(10)
	v_mfma_f32_16x16x32_bf16 v[42:45], v[72:75], v[64:67], 0
	s_waitcnt lgkmcnt(8)
	v_mfma_f32_16x16x32_bf16 v[46:49], v[80:83], v[76:79], v[46:49]
	s_waitcnt lgkmcnt(7)
	v_mfma_f32_16x16x32_bf16 v[42:45], v[84:87], v[76:79], v[42:45]
	s_waitcnt lgkmcnt(5)
	v_mfma_f32_16x16x32_bf16 v[46:49], v[92:95], v[88:91], v[46:49]
	s_waitcnt lgkmcnt(4)
	v_mfma_f32_16x16x32_bf16 v[42:45], v[96:99], v[88:91], v[42:45]
	s_waitcnt lgkmcnt(2)
	v_mfma_f32_16x16x32_bf16 v[46:49], v[104:107], v[100:103], v[46:49]
	s_waitcnt lgkmcnt(1)
	v_mfma_f32_16x16x32_bf16 v[42:45], v[108:111], v[100:103], v[42:45]
	s_waitcnt lgkmcnt(0)
	v_lshlrev_b32_e32 v52, 16, v62
	v_and_b32_e32 v53, 0xffff0000, v62
	v_lshlrev_b32_e32 v50, 16, v63
	v_and_b32_e32 v51, 0xffff0000, v63
	v_add_u32_e32 v41, v39, v38
	v_add_u32_e32 v54, s17, v29
	v_add_u32_e32 v55, s17, v9
	s_nop 3
	v_pk_add_f32 v[46:47], v[52:53], v[46:47] neg_lo:[0,1] neg_hi:[0,1]
	v_pk_add_f32 v[48:49], v[50:51], v[48:49] neg_lo:[0,1] neg_hi:[0,1]
	v_cvt_pk_bf16_f32 v46, v46, v47
	v_cvt_pk_bf16_f32 v47, v48, v49
	ds_write_b64 v30, v[46:47]
	v_add_u32_e32 v50, v54, v26
	v_add_u32_e32 v51, v54, v24
	v_add_u32_e32 v52, v55, v26
	v_add_u32_e32 v53, v55, v24
	v_mov_b32_e32 v61, s10
	s_waitcnt vmcnt(12)
	s_waitcnt lgkmcnt(0)
	s_barrier
	ds_read_b128 v[64:67], v41
	ds_read_b128 v[68:71], v50 offset:32768
	ds_read_b128 v[72:75], v41 offset:64
	ds_read_b128 v[76:79], v51 offset:32768
	ds_read_b32 v60, v61
	ds_read_b128 v[80:83], v52 offset:40960
	ds_read_b128 v[84:87], v28
	ds_read_b128 v[88:91], v53 offset:40960
	ds_read_b128 v[92:95], v28 offset:64
	ds_read_b128 v[96:99], v28 offset:2304
	ds_read_b128 v[100:103], v28 offset:2368
	s_cmpk_eq_i32 s11, 0x7f
	s_cbranch_scc1 .Lsc_noA
	s_mov_b64 s[18:19], 0x70000
	v_lshl_add_u64 v[20:21], v[20:21], 0, s[18:19]
	s_mov_b64 s[18:19], 0x30000
	v_lshl_add_u64 v[14:15], v[14:15], 0, s[18:19]
	v_lshl_add_u64 v[16:17], v[16:17], 0, s[18:19]
	s_add_i32 s18, s16, s17
	s_mov_b32 m0, s18
	s_mov_b64 s[22:23], 0x38000
	s_mov_b64 s[20:21], 0x18000
	v_lshl_add_u64 v[56:57], v[20:21], 0, s[4:5]
	v_lshl_add_u64 v[58:59], v[56:57], 0, s[22:23]
	global_load_lds_dwordx4 v[56:57], off
	s_add_u32 m0, m0, 0x2000
	v_lshl_add_u64 v[56:57], v[14:15], 0, s[4:5]
	global_load_lds_dwordx4 v[58:59], off
	s_add_u32 m0, m0, 0x2000
	v_lshl_add_u64 v[58:59], v[56:57], 0, s[20:21]
	global_load_lds_dwordx4 v[56:57], off
	s_add_u32 m0, m0, 0x2000
	s_nop 0
	global_load_lds_dwordx4 v[58:59], off
	s_andn2_b64 vcc, exec, s[8:9]
	s_cbranch_vccnz .Lscl_nou
	s_add_u32 m0, m0, 0x8000
	s_nop 0
	global_load_lds_dwordx4 v[16:17], off
	s_branch .Lscl_ud

; DI unsigned pk_bf16(float a, float b) { bf2_t v = __builtin_convertvector((f2_t){a, b}, bf2_t); return __builtin_bit_cast(unsigned, v); }
; DI u32x2 pack4(const f32x4 a) { u32x2 w; w.x = pk_bf16(a[0], a[1]); w.y = pk_bf16(a[2], a[3]); return w; }
; DI void lds_barrier() { asm volatile("s_waitcnt lgkmcnt(0)\n\ts_barrier" ::: "memory"); }
; DI void gdn_scan(const Params& P, int item, unsigned char* smem) {
;     ...
;         for (int ks = 0; ks < 2; ++ks) {
;             const bf16x8 vf = *(const bf16x8*)(VT + (16 * nt + r16) * 72 + 32 * ks + 8 * q4);
;             const bf16x8 qk = *(const bf16x8*)(sg + oqk + (((4 * ks + q4) ^ x8) << 4));
;             aO = __builtin_amdgcn_mfma_f32_16x16x32_bf16(qk, vf, aO, 0, 0, 0);
;         }
;         {
;             bf16_t* op = mixed + (tb + (size_t)c * 64 + 16 * mi + 4 * q4) * D + 256 + h * 128 + ns * 32 + 16 * nt + r16;
; #pragma unroll
;             for (int r = 0; r < 4; ++r) op[(size_t)r * D] = (bf16_t)(pk_bf16(aO[r], 0.f) & 0xffffu);
;         }
;         const float gl = gls[c];
;         bf16x8 kd[2];
; #pragma unroll
;         for (int ks = 0; ks < 2; ++ks) kd[ks] = *(const bf16x8*)(sg + okd + (((4 * ks + q4) ^ x8) << 4));
; #pragma unroll
;         for (int n2 = 0; n2 < 2; ++n2) {
;             accS[n2] = accS[n2] * gl;
; #pragma unroll
;             for (int ks = 0; ks < 2; ++ks) {
;                 const bf16x8 vf = *(const bf16x8*)(VT + (16 * n2 + r16) * 72 + 32 * ks + 8 * q4);
;                 accS[n2] = __builtin_amdgcn_mfma_f32_16x16x32_bf16(kd[ks], vf, accS[n2], 0, 0, 0);
;             }
;             *(u32x2*)(ST + (16 * n2 + r16) * 136 + 16 * md + 4 * q4) = pack4(accS[n2]);
;         }
;         asm volatile("s_waitcnt vmcnt(0)" ::: "memory");
;         lds_barrier();
;     }
.Lscl_ud:
.Lsc_noA:
	s_waitcnt lgkmcnt(9)
	v_mfma_f32_16x16x32_bf16 v[42:45], v[68:71], v[64:67], v[42:45]
	s_waitcnt lgkmcnt(7)
	v_mfma_f32_16x16x32_bf16 v[42:45], v[76:79], v[72:75], v[42:45]
	s_waitcnt lgkmcnt(6)
	v_pk_mul_f32 v[6:7], v[6:7], v[60:61] op_sel_hi:[1,0]
	v_pk_mul_f32 v[4:5], v[4:5], v[60:61] op_sel_hi:[1,0]
	v_pk_mul_f32 v[2:3], v[2:3], v[60:61] op_sel_hi:[1,0]
	v_pk_mul_f32 v[0:1], v[0:1], v[60:61] op_sel_hi:[1,0]
	s_waitcnt lgkmcnt(4)
	v_mfma_f32_16x16x32_bf16 v[4:7], v[80:83], v[84:87], v[4:7]
	s_waitcnt lgkmcnt(2)
	v_mfma_f32_16x16x32_bf16 v[4:7], v[88:91], v[92:95], v[4:7]
	s_waitcnt lgkmcnt(1)
	v_mfma_f32_16x16x32_bf16 v[0:3], v[80:83], v[96:99], v[0:3]
	s_waitcnt lgkmcnt(0)
	v_mfma_f32_16x16x32_bf16 v[0:3], v[88:91], v[100:103], v[0:3]
	v_lshl_add_u64 v[46:47], v[12:13], 0, s[4:5]
	v_add_co_u32_e32 v48, vcc, s0, v46
	v_cvt_pk_bf16_f32 v56, v42, s0
	v_cvt_pk_bf16_f32 v57, v43, s0
	v_addc_co_u32_e32 v49, vcc, 0, v47, vcc
	v_add_co_u32_e32 v50, vcc, s93, v46
	v_cvt_pk_bf16_f32 v58, v44, s0
	v_cvt_pk_bf16_f32 v59, v45, s0
	v_addc_co_u32_e32 v51, vcc, 0, v47, vcc
	global_store_short v[48:49], v56, off offset:512
	global_store_short v[48:49], v57, off offset:2560
	global_store_short v[50:51], v58, off offset:512
	global_store_short v[50:51], v59, off offset:2560
	s_mov_b64 s[18:19], 0x20000
	v_lshl_add_u64 v[12:13], v[12:13], 0, s[18:19]
	s_mov_b64 s[18:19], 0x70000
	v_cvt_pk_bf16_f32 v52, v4, v5
	v_cvt_pk_bf16_f32 v53, v6, v7
	ds_write_b64 v25, v[52:53]
	v_lshl_add_u64 v[18:19], v[18:19], 0, s[18:19]
	v_lshl_add_u64 v[22:23], v[22:23], 0, s[18:19]
	s_add_i32 s10, s10, 4
	v_cvt_pk_bf16_f32 v54, v0, v1
	v_cvt_pk_bf16_f32 v55, v2, v3
	ds_write_b64 v25, v[54:55] offset:4352
	s_cmpk_lg_i32 s11, 0x7f
	s_cbranch_scc0 .Lsc_last
	s_waitcnt vmcnt(12)
	s_waitcnt lgkmcnt(0)
	s_barrier
	s_mov_b32 s17, s11
	s_branch .LBB0_74
.Lsc_last:
	s_waitcnt vmcnt(0)
	s_waitcnt lgkmcnt(0)
	s_barrier
	s_mov_b32 s17, s11
	s_branch .LBB0_64
